# attention loop v2: softmax VALU spread evenly 4 per MFMA gap, map-split PV phases, DMA scalar setup before the barrier, no static priority raise
# speedup vs baseline: 1.0225x; 1.0225x over previous
; DI void phase_attn(const Params& p, char* lds, int l) {
;     ...
;   if (__builtin_amdgcn_readfirstlane(threadIdx.x) >= 256) __builtin_amdgcn_s_setprio(1);
.LBB0_715:
	s_or_b64 exec, exec, s[4:5]
	v_readfirstlane_b32 s4, v199
	s_cmpk_lt_i32 s4, 0x100
	s_cbranch_scc1 .LBB0_717
	s_setprio 0

; #define MFMA32(a, b, c) __builtin_amdgcn_mfma_f32_32x32x16_bf16((a), (b), (c), 0, 0, 0)
; #define WAIT_BAR0() asm volatile("s_waitcnt vmcnt(0) lgkmcnt(0)\n\ts_barrier" ::: "memory")
; #define DMA_TILE(kt_, so_) do { glds16(kgp + (size_t)(kt_) * 64 * 128, dk0 + (so_)); glds16(kgp + (size_t)(kt_) * 64 * 128 + 32 * 128, dk0 + (so_) + 8192); \
;     glds16(vgp + (kt_) * 64, dk0 + (so_) + 16384); glds16(vgp + (size_t)64 * SEQ + (kt_) * 64, dk0 + (so_) + 24576); } while (0)
; #define SOFTMAX_PACK(S_, P_, l_) do { _Pragma("unroll") for (int e = 0; e < 16; ++e) { S_[e] = __builtin_amdgcn_exp2f(S_[e]); l_ += S_[e]; } \
;         _Pragma("unroll") for (int s = 0; s < 2; ++s) { u32x4 a_; _Pragma("unroll") for (int q = 0; q < 4; ++q) a_[q] = cvtpk(S_[8 * s + 2 * q], S_[8 * s + 2 * q + 1]); P_[s] = __builtin_bit_cast(bf16x8, a_); } } while (0)
; DI void attn_item(const Params& p, char* lds, int l, int bh, int jt, float lam, float outscale) {
;     ...
;   for (int kt = 0; kt < nkt; ++kt) {
;     WAIT_BAR0();
;     const unsigned so = (kt & 1) * 32768;
;     if (kt + 1 < nkt) DMA_TILE(kt + 1, 32768 - so);
;     if (kt <= my_last) {
;     ...
;       bf16x8 pa0[2], pa1[2];
;       f32x16 S0, S1;
; #pragma unroll
;       for (int e = 0; e < 16; ++e) { S0[e] = 0.f; S1[e] = 0.f; }
; #pragma unroll
;       for (int ks = 0; ks < 4; ++ks) {
;         S0 = MFMA32(KFRAG(0, 0, ks), QFRAG(0, ks), S0);
;         S1 = MFMA32(KFRAG(0, 1, ks), QFRAG(1, ks), S1);
;       }
;       SOFTMAX_PACK(S0, pa0, l0);
;       SOFTMAX_PACK(S1, pa1, l1);
; #pragma unroll
;       for (int e = 0; e < 16; ++e) { S0[e] = 0.f; S1[e] = 0.f; }
; #pragma unroll
;       for (int ks = 0; ks < 4; ++ks) {
;         S0 = MFMA32(KFRAG(1, 0, ks), QFRAG(0, ks), S0);
;         S1 = MFMA32(KFRAG(1, 1, ks), QFRAG(1, ks), S1);
; #pragma unroll
;         for (int dd = 0; dd < 2; ++dd) {
;           const int d = (ks & 1) * 2 + dd, s = ks >> 1;
;           const bf16x8 vf = VFRAG(0, d, s);
;           O0[d] = MFMA32(vf, pa0[s], O0[d]);
;           O1[d] = MFMA32(vf, pa1[s], O1[d]);
;         }
;       }
;       bf16x8 pc0[2], pc1[2];
;       SOFTMAX_PACK(S0, pc0, l0);
;       SOFTMAX_PACK(S1, pc1, l1);
.LBB0_725:
	s_and_b32 s49, s26, 0x8000
	s_add_i32 s27, s35, 1
	s_lshr_b32 s50, s26, 1
	s_add_u32 s50, s16, s50
	s_addc_u32 s51, s17, 0
	s_lshl_b32 s52, s76, 1
	s_add_u32 s52, s12, s52
	s_addc_u32 s53, s13, 0
	s_sub_i32 s54, s19, s49
	s_add_i32 s54, s54, 0x8000
	s_waitcnt vmcnt(0) lgkmcnt(0)
	s_barrier
.LBB0_727:
	s_cmp_gt_i32 s35, s25
	s_cbranch_scc1 .Lattn_a_idle
	v_add_u32_e32 v203, s49, v252
	ds_read_b128 v[210:213], v251 offset:32768
	ds_read_b128 v[160:163], v203
	v_xor_b32_e32 v204, 0x20, v203
	ds_read_b128 v[214:217], v251 offset:40960
	ds_read_b128 v[164:167], v204
	v_xor_b32_e32 v205, 0x40, v203
	ds_read_b128 v[218:221], v251 offset:49152
	ds_read_b128 v[168:171], v205
	v_xor_b32_e32 v209, 0x60, v203
	ds_read_b128 v[222:225], v251 offset:57344
	ds_read_b128 v[172:175], v209
	v_xor_b32_e32 v235, 0x80, v203
	v_xor_b32_e32 v236, 0xa0, v203
	v_xor_b32_e32 v237, 0xc0, v203
	v_xor_b32_e32 v244, 0xe0, v203
	s_waitcnt lgkmcnt(6)
	v_mfma_f32_32x32x16_bf16 v[144:159], v[160:163], v[210:213], 0
	ds_read_b128 v[226:229], v251
	ds_read_b128 v[160:163], v235
	s_cmp_ge_i32 s27, s24
	s_cbranch_scc1 .Ldma_skip_1
	s_mov_b32 m0, s54
	s_nop 0
	global_load_lds_dwordx4 v208, s[50:51]
.Ldma_skip_1:
	s_waitcnt lgkmcnt(6)
	v_mfma_f32_32x32x16_bf16 v[144:159], v[164:167], v[214:217], v[144:159]
	ds_read_b128 v[230:233], v251 offset:8192
	ds_read_b128 v[164:167], v236
	s_cmp_ge_i32 s27, s24
	s_cbranch_scc1 .Ldma_skip_2
	s_add_u32 s50, s50, 0x2000
	s_addc_u32 s51, s51, 0
	s_add_i32 s54, s54, 0x2000
	s_mov_b32 m0, s54
	s_nop 0
	global_load_lds_dwordx4 v208, s[50:51]
.Ldma_skip_2:
	s_waitcnt lgkmcnt(6)
	v_mfma_f32_32x32x16_bf16 v[144:159], v[168:171], v[218:221], v[144:159]
	ds_read_b128 v[240:243], v251 offset:16384
	ds_read_b128 v[168:171], v237
	s_cmp_ge_i32 s27, s24
	s_cbranch_scc1 .Ldma_skip_3
	s_add_i32 s54, s54, 0x2000
	s_mov_b32 m0, s54
	s_nop 0
	global_load_lds_dwordx4 v202, s[52:53]
.Ldma_skip_3:
	s_waitcnt lgkmcnt(6)
	v_mfma_f32_32x32x16_bf16 v[144:159], v[172:175], v[222:225], v[144:159]
	ds_read_b128 v[192:195], v251 offset:24576
	ds_read_b128 v[172:175], v244
	s_cmp_ge_i32 s27, s24
	s_cbranch_scc1 .Ldma_skip_4
	s_add_u32 s52, s52, 0x200000
	s_addc_u32 s53, s53, 0
	s_add_i32 s54, s54, 0x2000
	s_mov_b32 m0, s54
	s_nop 0
	global_load_lds_dwordx4 v202, s[52:53]
.Ldma_skip_4:
	s_waitcnt lgkmcnt(6)
	v_mfma_f32_32x32x16_bf16 v[128:143], v[160:163], v[226:229], 0
	ds_read_b128 v[176:179], v203 offset:8192
	v_exp_f32_e32 v144, v144
	v_exp_f32_e32 v145, v145
	v_add_f32_e32 v207, v207, v144
	v_add_f32_e32 v207, v207, v145
	s_waitcnt lgkmcnt(5)
	v_mfma_f32_32x32x16_bf16 v[128:143], v[164:167], v[230:233], v[128:143]
	ds_read_b128 v[180:183], v204 offset:8192
	v_cvt_pk_bf16_f32 v144, v144, v145
	v_exp_f32_e32 v146, v146
	v_exp_f32_e32 v147, v147
	v_add_f32_e32 v207, v207, v146
	s_waitcnt lgkmcnt(4)
	v_mfma_f32_32x32x16_bf16 v[128:143], v[168:171], v[240:243], v[128:143]
	ds_read_b128 v[184:187], v205 offset:8192
	v_add_f32_e32 v207, v207, v147
	v_cvt_pk_bf16_f32 v145, v146, v147
	v_exp_f32_e32 v148, v148
	v_exp_f32_e32 v149, v149
	s_waitcnt lgkmcnt(3)
	v_mfma_f32_32x32x16_bf16 v[128:143], v[172:175], v[192:195], v[128:143]
	ds_read_b128 v[188:191], v209 offset:8192
	v_add_f32_e32 v207, v207, v148
	v_add_f32_e32 v207, v207, v149
	v_cvt_pk_bf16_f32 v146, v148, v149
	v_exp_f32_e32 v150, v150
	s_waitcnt lgkmcnt(3)
	v_mfma_f32_32x32x16_bf16 v[160:175], v[176:179], v[210:213], 0
	ds_read_b128 v[210:213], v235 offset:8192
	v_exp_f32_e32 v151, v151
	v_add_f32_e32 v207, v207, v150
	v_add_f32_e32 v207, v207, v151
	v_cvt_pk_bf16_f32 v147, v150, v151
	s_waitcnt lgkmcnt(3)
	v_mfma_f32_32x32x16_bf16 v[160:175], v[180:183], v[214:217], v[160:175]
	ds_read_b128 v[214:217], v236 offset:8192
	v_exp_f32_e32 v128, v128
	v_exp_f32_e32 v129, v129
	v_add_f32_e32 v206, v206, v128
	v_add_f32_e32 v206, v206, v129
	s_waitcnt lgkmcnt(3)
	v_mfma_f32_32x32x16_bf16 v[160:175], v[184:187], v[218:221], v[160:175]
	ds_read_b128 v[218:221], v237 offset:8192
	v_cvt_pk_bf16_f32 v128, v128, v129
	v_exp_f32_e32 v130, v130
	v_exp_f32_e32 v131, v131
	v_add_f32_e32 v206, v206, v130
	s_waitcnt lgkmcnt(3)
	v_mfma_f32_32x32x16_bf16 v[160:175], v[188:191], v[222:225], v[160:175]
	ds_read_b128 v[222:225], v244 offset:8192
	v_add_f32_e32 v206, v206, v131
	v_cvt_pk_bf16_f32 v129, v130, v131
	v_exp_f32_e32 v132, v132
	v_exp_f32_e32 v133, v133
	v_add_u32_e32 v203, s49, v253
	v_xor_b32_e32 v204, 0x20, v203
	v_xor_b32_e32 v205, 0x40, v203
	v_xor_b32_e32 v209, 0x60, v203
	s_waitcnt lgkmcnt(3)
	v_mfma_f32_32x32x16_bf16 v[176:191], v[210:213], v[226:229], 0
	ds_read_b128 v[226:229], v203 offset:16384
	v_add_f32_e32 v206, v206, v132
	v_add_f32_e32 v206, v206, v133
	v_cvt_pk_bf16_f32 v130, v132, v133
	v_exp_f32_e32 v134, v134
	s_waitcnt lgkmcnt(3)
	v_mfma_f32_32x32x16_bf16 v[176:191], v[214:217], v[230:233], v[176:191]
	ds_read_b128 v[230:233], v203 offset:20480
	v_exp_f32_e32 v135, v135
	v_add_f32_e32 v206, v206, v134
	v_add_f32_e32 v206, v206, v135
	v_cvt_pk_bf16_f32 v131, v134, v135
	s_waitcnt lgkmcnt(3)
	v_mfma_f32_32x32x16_bf16 v[176:191], v[218:221], v[240:243], v[176:191]
	ds_read_b128 v[240:243], v203 offset:24576
	v_exp_f32_e32 v152, v152
	v_exp_f32_e32 v153, v153
	v_add_f32_e32 v207, v207, v152
	v_add_f32_e32 v207, v207, v153
	s_waitcnt lgkmcnt(3)
	v_mfma_f32_32x32x16_bf16 v[176:191], v[222:225], v[192:195], v[176:191]
	ds_read_b128 v[192:195], v203 offset:28672
	v_cvt_pk_bf16_f32 v148, v152, v153
	v_exp_f32_e32 v154, v154
	v_exp_f32_e32 v155, v155
	v_add_f32_e32 v207, v207, v154
	s_waitcnt lgkmcnt(3)
; #define MFMA32(a, b, c) __builtin_amdgcn_mfma_f32_32x32x16_bf16((a), (b), (c), 0, 0, 0)
; #define SOFTMAX_PACK(S_, P_, l_) do { _Pragma("unroll") for (int e = 0; e < 16; ++e) { S_[e] = __builtin_amdgcn_exp2f(S_[e]); l_ += S_[e]; } \
;         _Pragma("unroll") for (int s = 0; s < 2; ++s) { u32x4 a_; _Pragma("unroll") for (int q = 0; q < 4; ++q) a_[q] = cvtpk(S_[8 * s + 2 * q], S_[8 * s + 2 * q + 1]); P_[s] = __builtin_bit_cast(bf16x8, a_); } } while (0)
; DI void attn_item(const Params& p, char* lds, int l, int bh, int jt, float lam, float outscale) {
;     ...
;       SOFTMAX_PACK(S0, pa0, l0);
;       SOFTMAX_PACK(S1, pa1, l1);
; #pragma unroll
;       for (int e = 0; e < 16; ++e) { S0[e] = 0.f; S1[e] = 0.f; }
; #pragma unroll
;       for (int ks = 0; ks < 4; ++ks) {
;         S0 = MFMA32(KFRAG(1, 0, ks), QFRAG(0, ks), S0);
;         S1 = MFMA32(KFRAG(1, 1, ks), QFRAG(1, ks), S1);
; #pragma unroll
;         for (int dd = 0; dd < 2; ++dd) {
;           const int d = (ks & 1) * 2 + dd, s = ks >> 1;
;           const bf16x8 vf = VFRAG(0, d, s);
;           O0[d] = MFMA32(vf, pa0[s], O0[d]);
;           O1[d] = MFMA32(vf, pa1[s], O1[d]);
;         }
;       }
;       bf16x8 pc0[2], pc1[2];
;       SOFTMAX_PACK(S0, pc0, l0);
;       SOFTMAX_PACK(S1, pc1, l1);
; #pragma unroll
;       for (int s = 0; s < 2; ++s) {
; #pragma unroll
;         for (int d = 0; d < 4; ++d) {
;           const bf16x8 vf = VFRAG(1, d, s);
;           O0[d] = MFMA32(vf, pc0[s], O0[d]);
;           O1[d] = MFMA32(vf, pc1[s], O1[d]);
;         }
;       }
	v_mfma_f32_32x32x16_bf16 v[112:127], v[226:229], v[144:147], v[112:127]
	ds_read_b128 v[210:213], v204 offset:16384
	v_add_f32_e32 v207, v207, v155
	v_cvt_pk_bf16_f32 v149, v154, v155
	v_exp_f32_e32 v156, v156
	v_exp_f32_e32 v157, v157
	s_waitcnt lgkmcnt(3)
	v_mfma_f32_32x32x16_bf16 v[64:79], v[230:233], v[144:147], v[64:79]
	ds_read_b128 v[214:217], v204 offset:20480
	v_add_f32_e32 v207, v207, v156
	v_add_f32_e32 v207, v207, v157
	v_cvt_pk_bf16_f32 v150, v156, v157
	v_exp_f32_e32 v158, v158
	s_waitcnt lgkmcnt(3)
	v_mfma_f32_32x32x16_bf16 v[32:47], v[240:243], v[144:147], v[32:47]
	ds_read_b128 v[218:221], v204 offset:24576
	v_exp_f32_e32 v159, v159
	v_add_f32_e32 v207, v207, v158
	v_add_f32_e32 v207, v207, v159
	v_cvt_pk_bf16_f32 v151, v158, v159
	s_waitcnt lgkmcnt(3)
	v_mfma_f32_32x32x16_bf16 v[0:15], v[192:195], v[144:147], v[0:15]
	ds_read_b128 v[222:225], v204 offset:28672
	v_exp_f32_e32 v136, v136
	v_exp_f32_e32 v137, v137
	v_add_f32_e32 v206, v206, v136
	v_add_f32_e32 v206, v206, v137
	v_mfma_f32_32x32x16_bf16 v[96:111], v[226:229], v[128:131], v[96:111]
	v_cvt_pk_bf16_f32 v132, v136, v137
	v_exp_f32_e32 v138, v138
	v_exp_f32_e32 v139, v139
	v_add_f32_e32 v206, v206, v138
	v_mfma_f32_32x32x16_bf16 v[80:95], v[230:233], v[128:131], v[80:95]
	v_add_f32_e32 v206, v206, v139
	v_cvt_pk_bf16_f32 v133, v138, v139
	v_exp_f32_e32 v140, v140
	v_exp_f32_e32 v141, v141
	v_mfma_f32_32x32x16_bf16 v[48:63], v[240:243], v[128:131], v[48:63]
	v_add_f32_e32 v206, v206, v140
	v_add_f32_e32 v206, v206, v141
	v_cvt_pk_bf16_f32 v134, v140, v141
	v_exp_f32_e32 v142, v142
	v_mfma_f32_32x32x16_bf16 v[16:31], v[192:195], v[128:131], v[16:31]
	v_exp_f32_e32 v143, v143
	v_add_f32_e32 v206, v206, v142
	v_add_f32_e32 v206, v206, v143
	v_cvt_pk_bf16_f32 v135, v142, v143
	s_waitcnt lgkmcnt(3)
	v_mfma_f32_32x32x16_bf16 v[112:127], v[210:213], v[148:151], v[112:127]
	ds_read_b128 v[226:229], v205 offset:16384
	v_exp_f32_e32 v160, v160
	v_exp_f32_e32 v161, v161
	v_add_f32_e32 v207, v207, v160
	v_add_f32_e32 v207, v207, v161
	s_waitcnt lgkmcnt(3)
	v_mfma_f32_32x32x16_bf16 v[64:79], v[214:217], v[148:151], v[64:79]
	ds_read_b128 v[230:233], v205 offset:20480
	v_cvt_pk_bf16_f32 v160, v160, v161
	v_exp_f32_e32 v162, v162
	v_exp_f32_e32 v163, v163
	v_add_f32_e32 v207, v207, v162
	s_waitcnt lgkmcnt(3)
	v_mfma_f32_32x32x16_bf16 v[32:47], v[218:221], v[148:151], v[32:47]
	ds_read_b128 v[240:243], v205 offset:24576
	v_add_f32_e32 v207, v207, v163
	v_cvt_pk_bf16_f32 v161, v162, v163
	v_exp_f32_e32 v164, v164
	v_exp_f32_e32 v165, v165
	s_waitcnt lgkmcnt(3)
	v_mfma_f32_32x32x16_bf16 v[0:15], v[222:225], v[148:151], v[0:15]
	ds_read_b128 v[192:195], v205 offset:28672
	v_add_f32_e32 v207, v207, v164
	v_add_f32_e32 v207, v207, v165
	v_cvt_pk_bf16_f32 v162, v164, v165
	v_exp_f32_e32 v166, v166
	v_mfma_f32_32x32x16_bf16 v[96:111], v[210:213], v[132:135], v[96:111]
	v_exp_f32_e32 v167, v167
	v_add_f32_e32 v207, v207, v166
	v_add_f32_e32 v207, v207, v167
	v_cvt_pk_bf16_f32 v163, v166, v167
	v_mfma_f32_32x32x16_bf16 v[80:95], v[214:217], v[132:135], v[80:95]
	v_exp_f32_e32 v176, v176
	v_exp_f32_e32 v177, v177
	v_add_f32_e32 v206, v206, v176
	v_add_f32_e32 v206, v206, v177
	v_mfma_f32_32x32x16_bf16 v[48:63], v[218:221], v[132:135], v[48:63]
	v_cvt_pk_bf16_f32 v176, v176, v177
	v_exp_f32_e32 v178, v178
	v_exp_f32_e32 v179, v179
	v_add_f32_e32 v206, v206, v178
	v_mfma_f32_32x32x16_bf16 v[16:31], v[222:225], v[132:135], v[16:31]
	v_add_f32_e32 v206, v206, v179
	v_cvt_pk_bf16_f32 v177, v178, v179
	v_exp_f32_e32 v180, v180
	v_exp_f32_e32 v181, v181
	s_waitcnt lgkmcnt(3)
	v_mfma_f32_32x32x16_bf16 v[112:127], v[226:229], v[160:163], v[112:127]
	ds_read_b128 v[210:213], v209 offset:16384
	v_add_f32_e32 v206, v206, v180
	v_add_f32_e32 v206, v206, v181
	v_cvt_pk_bf16_f32 v178, v180, v181
	v_exp_f32_e32 v182, v182
	s_waitcnt lgkmcnt(3)
	v_mfma_f32_32x32x16_bf16 v[64:79], v[230:233], v[160:163], v[64:79]
	ds_read_b128 v[214:217], v209 offset:20480
	v_exp_f32_e32 v183, v183
	v_add_f32_e32 v206, v206, v182
	v_add_f32_e32 v206, v206, v183
	v_cvt_pk_bf16_f32 v179, v182, v183
	s_waitcnt lgkmcnt(3)
	v_mfma_f32_32x32x16_bf16 v[32:47], v[240:243], v[160:163], v[32:47]
	ds_read_b128 v[218:221], v209 offset:24576
	v_exp_f32_e32 v168, v168
	v_exp_f32_e32 v169, v169
	v_add_f32_e32 v207, v207, v168
	v_add_f32_e32 v207, v207, v169
	s_waitcnt lgkmcnt(3)
	v_mfma_f32_32x32x16_bf16 v[0:15], v[192:195], v[160:163], v[0:15]
	ds_read_b128 v[222:225], v209 offset:28672
	v_cvt_pk_bf16_f32 v164, v168, v169
	v_exp_f32_e32 v170, v170
	v_exp_f32_e32 v171, v171
	v_add_f32_e32 v207, v207, v170
	v_mfma_f32_32x32x16_bf16 v[96:111], v[226:229], v[176:179], v[96:111]
	v_add_f32_e32 v207, v207, v171
	v_cvt_pk_bf16_f32 v165, v170, v171
	v_exp_f32_e32 v172, v172
	v_exp_f32_e32 v173, v173
	v_mfma_f32_32x32x16_bf16 v[80:95], v[230:233], v[176:179], v[80:95]
	v_add_f32_e32 v207, v207, v172
	v_add_f32_e32 v207, v207, v173
	v_cvt_pk_bf16_f32 v166, v172, v173
	v_exp_f32_e32 v174, v174
	v_mfma_f32_32x32x16_bf16 v[48:63], v[240:243], v[176:179], v[48:63]
	v_exp_f32_e32 v175, v175
	v_add_f32_e32 v207, v207, v174
	v_add_f32_e32 v207, v207, v175
	v_cvt_pk_bf16_f32 v167, v174, v175
	v_mfma_f32_32x32x16_bf16 v[16:31], v[192:195], v[176:179], v[16:31]
	v_exp_f32_e32 v184, v184
	v_exp_f32_e32 v185, v185
	v_add_f32_e32 v206, v206, v184
	v_add_f32_e32 v206, v206, v185
	s_waitcnt lgkmcnt(3)
	v_mfma_f32_32x32x16_bf16 v[112:127], v[210:213], v[164:167], v[112:127]
	v_cvt_pk_bf16_f32 v180, v184, v185
	v_exp_f32_e32 v186, v186
	v_exp_f32_e32 v187, v187
	v_add_f32_e32 v206, v206, v186
	s_waitcnt lgkmcnt(2)
	v_mfma_f32_32x32x16_bf16 v[64:79], v[214:217], v[164:167], v[64:79]
	v_add_f32_e32 v206, v206, v187
	v_cvt_pk_bf16_f32 v181, v186, v187
	v_exp_f32_e32 v188, v188
	v_exp_f32_e32 v189, v189
	s_waitcnt lgkmcnt(1)
	v_mfma_f32_32x32x16_bf16 v[32:47], v[218:221], v[164:167], v[32:47]
	v_add_f32_e32 v206, v206, v188
	v_add_f32_e32 v206, v206, v189
	v_cvt_pk_bf16_f32 v182, v188, v189
	v_exp_f32_e32 v190, v190
	s_waitcnt lgkmcnt(0)
	v_mfma_f32_32x32x16_bf16 v[0:15], v[222:225], v[164:167], v[0:15]
	v_exp_f32_e32 v191, v191
	v_add_f32_e32 v206, v206, v190
	v_add_f32_e32 v206, v206, v191
	v_cvt_pk_bf16_f32 v183, v190, v191
	s_nop 1
	v_mfma_f32_32x32x16_bf16 v[96:111], v[210:213], v[180:183], v[96:111]
	v_mfma_f32_32x32x16_bf16 v[80:95], v[214:217], v[180:183], v[80:95]
	v_mfma_f32_32x32x16_bf16 v[48:63], v[218:221], v[180:183], v[48:63]
	v_mfma_f32_32x32x16_bf16 v[16:31], v[222:225], v[180:183], v[16:31]

; #define DMA_TILE(kt_, so_) do { glds16(kgp + (size_t)(kt_) * 64 * 128, dk0 + (so_)); glds16(kgp + (size_t)(kt_) * 64 * 128 + 32 * 128, dk0 + (so_) + 8192); \
;     glds16(vgp + (kt_) * 64, dk0 + (so_) + 16384); glds16(vgp + (size_t)64 * SEQ + (kt_) * 64, dk0 + (so_) + 24576); } while (0)
; DI void attn_item(const Params& p, char* lds, int l, int bh, int jt, float lam, float outscale) {
;     ...
;     if (kt + 1 < nkt) DMA_TILE(kt + 1, 32768 - so);
.Lattn_a_idle:
	s_cmp_ge_i32 s27, s24
	s_cbranch_scc1 .Ldma_skip_5
	s_mov_b32 m0, s54
	s_nop 0
	global_load_lds_dwordx4 v208, s[50:51]
.Ldma_skip_5:
	s_cmp_ge_i32 s27, s24
	s_cbranch_scc1 .Ldma_skip_6
	s_add_u32 s50, s50, 0x2000
	s_addc_u32 s51, s51, 0
	s_add_i32 s54, s54, 0x2000
	s_mov_b32 m0, s54
	s_nop 0
	global_load_lds_dwordx4 v208, s[50:51]
.Ldma_skip_6:
	s_cmp_ge_i32 s27, s24
	s_cbranch_scc1 .Ldma_skip_7
	s_add_i32 s54, s54, 0x2000
	s_mov_b32 m0, s54
	s_nop 0
	global_load_lds_dwordx4 v202, s[52:53]
.Ldma_skip_7:
	s_cmp_ge_i32 s27, s24
	s_cbranch_scc1 .Ldma_skip_8
	s_add_u32 s52, s52, 0x200000
	s_addc_u32 s53, s53, 0
	s_add_i32 s54, s54, 0x2000
	s_mov_b32 m0, s54
	s_nop 0
	global_load_lds_dwordx4 v202, s[52:53]
